# mem_attn units dealt over all 256 WGs (scan WGs take 2 big units), reversed order
# baseline (speedup 1.0000x reference)
.LBB0_1796:
	s_waitcnt lgkmcnt(0)
	v_mov_b32_e32 v2, s13
	v_mov_b32_e32 v0, v230
	v_mov_b32_e32 v3, s12
	s_barrier
	s_nop 0
	v_readfirstlane_b32 s4, v3
	v_readfirstlane_b32 s5, v2
	v_mov_b32_e32 v2, s35
	v_mov_b32_e32 v3, s36
	v_readfirstlane_b32 s6, v0
	v_readfirstlane_b32 s36, v2
	v_readfirstlane_b32 s37, v3
	v_mov_b32_e32 v2, s24
	v_mov_b32_e32 v3, s34
	s_nop 0
	v_readfirstlane_b32 s34, v2
	v_readfirstlane_b32 s35, v3
	v_mov_b32_e32 v2, s25
	v_mov_b32_e32 v3, s38
	s_nop 0
	v_readfirstlane_b32 s24, v2
	v_mov_b32_e32 v2, v233
	v_readfirstlane_b32 s25, v3
	v_readfirstlane_b32 s7, v2
	v_mov_b32_e32 v2, v228
	s_nop 0
	v_readfirstlane_b32 s8, v2
	s_sub_i32 s9, s8, 32
	s_cmp_gt_i32 s7, 64
	s_cselect_b64 s[0:1], -1, 0
	s_and_b64 s[2:3], s[0:1], exec
	s_cselect_b32 s9, s9, s8
	s_cmp_lt_i32 s9, 0
	s_cselect_b32 s2, s7, 0
	s_add_i32 s9, s9, s2
	s_sub_i32 s9, s7, s9
	s_add_i32 s9, s9, -1
	s_cmpk_lt_u32 s9, 0x280
	s_mov_b64 s[2:3], -1
	s_cbranch_scc1 .LBB0_1798
	v_readlane_b32 s2, v253, 36
	v_readlane_b32 s3, v253, 37
	s_mov_b32 s3, s29
	v_writelane_b32 v253, s2, 36
	s_nop 1
	v_writelane_b32 v253, s3, 37
	s_mov_b64 s[2:3], 0
.LBB0_1798:
	s_andn2_b64 vcc, exec, s[2:3]
	v_xor_b32_e32 v132, 32, v229
	s_cbranch_vccnz .LBB0_1856
	s_add_u32 s38, s4, 0x2d7da000
	s_addc_u32 s39, s5, 0
	s_add_u32 s40, s4, 0x3efda000
	s_addc_u32 s41, s5, 0
	s_add_u32 s42, s4, 0x403da000
	v_cmp_lt_i32_e32 vcc, v130, v131
	s_addc_u32 s43, s5, 0
	s_add_u32 s44, s4, 0x2b552000
	v_cndmask_b32_e32 v2, v229, v130, vcc
	v_cmp_lt_i32_e32 vcc, v132, v131
	v_lshlrev_b32_e32 v85, 2, v2
	s_addc_u32 s45, s5, 0
	v_cndmask_b32_e32 v2, v229, v132, vcc
	s_sub_i32 s2, s7, 32
	v_lshlrev_b32_e32 v87, 2, v2
	v_and_b32_e32 v2, 15, v0
	v_bfe_u32 v3, v0, 4, 2
	s_and_b64 s[0:1], s[0:1], exec
	v_mul_u32_u24_e32 v8, 0x110, v2
	v_mul_u32_u24_e32 v2, 0x90, v2
	v_lshlrev_b32_e32 v84, 3, v3
	v_lshlrev_b32_e32 v6, 3, v0
	s_mov_b32 s46, s7
	s_ashr_i32 s0, s6, 2
	v_and_b32_e32 v4, 48, v0
	v_lshl_add_u32 v114, v84, 1, v2
	v_ashrrev_i32_e32 v2, 3, v0
	s_movk_i32 s6, 0x90
	v_and_b32_e32 v86, 56, v6
	v_add_u32_e32 v9, 0x200, v0
	v_add_u32_e32 v5, 0, v4
	v_lshlrev_b32_e32 v4, 2, v3
	v_mul_lo_u32 v3, v2, s6
	v_lshlrev_b32_e32 v7, 1, v86
	v_ashrrev_i32_e32 v6, 3, v9
	v_add3_u32 v118, 0, v3, v7
	v_mul_lo_u32 v3, v6, s6
	v_add3_u32 v119, 0, v3, v7
	v_and_b32_e32 v7, 1, v0
	v_lshl_add_u32 v118, v7, 4, v118
	v_lshl_add_u32 v119, v7, 4, v119
	v_bfe_u32 v7, v0, 1, 1
	v_mul_u32_u24_e32 v7, 24, v7
	v_sub_u32_e32 v118, v118, v7
	v_sub_u32_e32 v119, v119, v7
	v_ashrrev_i32_e32 v3, 31, v2
	v_lshlrev_b64 v[88:89], 9, v[2:3]
	v_ashrrev_i32_e32 v2, 31, v0
	v_lshrrev_b32_e32 v2, 28, v2
	v_add_u32_e32 v3, v0, v2
	v_ashrrev_i32_e32 v7, 31, v6
	v_ashrrev_i32_e32 v2, 4, v3
	s_movk_i32 s6, 0x110
	v_lshlrev_b64 v[90:91], 9, v[6:7]
	v_mul_lo_u32 v6, v2, s6
	v_add_u32_e32 v120, 0, v6
	v_ashrrev_i32_e32 v6, 31, v9
	v_lshrrev_b32_e32 v6, 28, v6
	v_and_b32_e32 v3, -16, v3
	v_add_u32_e32 v7, v9, v6
	v_sub_u32_e32 v3, v0, v3
	v_ashrrev_i32_e32 v6, 4, v7
	v_and_b32_e32 v7, -16, v7
	v_lshlrev_b32_e32 v121, 4, v3
	v_sub_u32_e32 v7, v9, v7
	v_lshlrev_b32_e32 v92, 3, v3
	v_ashrrev_i32_e32 v3, 31, v2
	s_movk_i32 s2, 0x200
	v_lshlrev_b32_e32 v123, 4, v7
	v_ashrrev_i32_e32 v93, 31, v92
	v_lshlrev_b32_e32 v94, 3, v7
	v_lshlrev_b64 v[98:99], 8, v[2:3]
	v_ashrrev_i32_e32 v7, 31, v6
	v_bfi_b32 v82, -16, s0, v0
	v_cmp_gt_i32_e64 s[0:1], s95, v0
	v_cmp_gt_i32_e64 s[2:3], s2, v0
	v_mul_lo_u32 v10, v6, s6
	v_ashrrev_i32_e32 v95, 31, v94
	v_lshlrev_b64 v[100:101], 8, v[6:7]
	v_lshl_add_u64 v[2:3], v[92:93], 1, v[98:99]
	s_mov_b64 s[6:7], 0x3efde000
	v_lshlrev_b32_e32 v0, 4, v0
	v_readlane_b32 s12, v253, 36
	v_lshl_add_u64 v[102:103], v[2:3], 0, s[6:7]
	v_lshl_add_u64 v[2:3], v[94:95], 1, v[100:101]
	v_and_b32_e32 v0, 0x70, v0
	v_readlane_b32 s13, v253, 37
	v_lshl_add_u64 v[104:105], v[2:3], 0, s[6:7]
	v_or_b32_e32 v2, v88, v0
	v_mov_b32_e32 v3, v89
	s_mov_b64 s[6:7], 0x403da080
	s_mov_b32 s13, s29
	v_lshl_add_u64 v[106:107], v[2:3], 0, s[6:7]
	v_or_b32_e32 v2, v90, v0
	v_mov_b32_e32 v3, v91
	s_mul_i32 s47, s12, 40
	v_ashrrev_i32_e32 v83, 31, v82
	v_writelane_b32 v253, s12, 36
	v_lshl_add_u64 v[108:109], v[2:3], 0, s[6:7]
	v_mov_b32_e32 v2, 0
	v_mov_b32_e32 v58, 0
	v_add_u32_e32 v115, 0x900, v114
	v_add_u32_e32 v116, 0x1200, v114
	v_add_u32_e32 v117, 0x1b00, v114
	v_add_u32_e32 v122, 0, v10
	v_lshlrev_b64 v[96:97], 10, v[82:83]
	v_writelane_b32 v253, s13, 37
	s_mov_b64 s[18:19], 0
	v_lshlrev_b32_e32 v110, 1, v4
	v_add_u32_e32 v83, v5, v8
	v_mov_b32_e32 v59, v58
	v_mov_b32_e32 v60, v58
	v_mov_b32_e32 v61, v58
	v_mov_b32_e32 v66, v58
	v_mov_b32_e32 v67, v58
	v_mov_b32_e32 v68, v58
	v_mov_b32_e32 v69, v58
	v_mov_b32_e32 v74, v58
	v_mov_b32_e32 v75, v58
	v_mov_b32_e32 v76, v58
	v_mov_b32_e32 v77, v58
	v_mov_b32_e32 v78, v58
	v_mov_b32_e32 v79, v58
	v_mov_b32_e32 v80, v58
	v_mov_b32_e32 v81, v58
	v_mov_b32_e32 v3, v2
	v_mov_b32_e32 v4, v2
	v_mov_b32_e32 v5, v2
	v_mov_b32_e32 v6, v2
	v_mov_b32_e32 v7, v2
	v_mov_b32_e32 v8, v2
	v_mov_b32_e32 v9, v2
	v_mov_b32_e32 v10, v2
	v_mov_b32_e32 v11, v2
	v_mov_b32_e32 v12, v2
	v_mov_b32_e32 v13, v2
	v_mov_b32_e32 v14, v2
	v_mov_b32_e32 v15, v2
	v_mov_b32_e32 v16, v2
	v_mov_b32_e32 v17, v2
	s_branch .LBB0_1801
